# phase 0: hand-written weight-transpose loop, next item's loads issued right after the LDS writes (scalar item decode, no per-load branches)
# baseline (speedup 1.0000x reference)
.LBB0_92:
	v_lshl_add_u32 v20, s2, 3, v145
	s_waitcnt lgkmcnt(0)
	s_barrier
	s_cmp_lg_u32 s70, 0x100
	s_cbranch_scc1 .Lp0_skip
	v_readfirstlane_b32 s72, v20
	v_and_b32_e32 v200, 31, v144
	v_lshlrev_b32_e32 v100, 2, v200
	v_lshrrev_b32_e32 v101, 5, v144
	v_lshlrev_b32_e32 v201, 14, v145
	v_mul_u32_u24_e32 v202, 0x84, v101
	v_add3_u32 v102, v201, v202, v100
	v_and_b32_e32 v200, 7, v144
	v_lshrrev_b32_e32 v105, 3, v144
	v_mul_u32_u24_e32 v202, 0x420, v200
	v_lshlrev_b32_e32 v203, 2, v105
	v_add3_u32 v103, v201, v202, v203
	v_lshlrev_b32_e32 v104, 4, v200
	v_mov_b32_e32 v106, 0x80
	s_movk_i32 s73, 24
	s_cmp_lt_u32 s72, 0x800
	s_cbranch_scc1 .Lp0_m0_a
	s_cmp_lt_u32 s72, 0x1800
	s_cbranch_scc1 .Lp0_m1_a
	s_cmp_lt_u32 s72, 0x4400
	s_cbranch_scc1 .Lp0_m2_a
	s_cmp_lt_u32 s72, 0x7000
	s_cbranch_scc1 .Lp0_m3_a
	s_cmp_lt_u32 s72, 0x8600
	s_cbranch_scc1 .Lp0_m4_a
	s_cmp_lt_u32 s72, 0x9c00
	s_cbranch_scc1 .Lp0_m5_a
	s_cmp_lt_u32 s72, 0xb860
	s_cbranch_scc1 .Lp0_m6_a
	s_sub_u32 s74, s72, 0xb860
	s_mov_b64 s[76:77], s[22:23]
	s_add_u32 s78, s30, 0xe800000
	s_addc_u32 s79, s31, 0
	s_movk_i32 s80, 0x800
	s_movk_i32 s81, 0x800
	s_mov_b32 s82, 0
	s_movk_i32 s83, 0x0
	s_lshr_b32 s84, s74, 6
	s_and_b32 s85, s74, 63
	s_branch .Lp0_dd_a
.Lp0_m0_a:
	s_mov_b32 s74, s72
	s_mov_b64 s[76:77], s[50:51]
	s_add_u32 s78, s30, 0x2f00000
	s_addc_u32 s79, s31, 0
	s_movk_i32 s80, 0x800
	s_movk_i32 s81, 0x800
	s_mov_b32 s82, 0
	s_movk_i32 s83, 0x0
	s_lshr_b32 s84, s74, 6
	s_and_b32 s85, s74, 63
	s_branch .Lp0_dd_a
.Lp0_m1_a:
	s_sub_u32 s74, s72, 0x800
	s_mov_b64 s[76:77], s[16:17]
	s_add_u32 s78, s30, 0x3700000
	s_addc_u32 s79, s31, 0
	s_movk_i32 s80, 0x800
	s_movk_i32 s81, 0x1000
	s_mov_b32 s82, 1
	s_movk_i32 s83, 0x800
	s_lshr_b32 s84, s74, 7
	s_and_b32 s85, s74, 127
	s_branch .Lp0_dd_a
.Lp0_m2_a:
	s_sub_u32 s74, s72, 0x1800
	s_mov_b64 s[76:77], s[24:25]
	s_add_u32 s78, s30, 0x4700000
	s_addc_u32 s79, s31, 0
	s_movk_i32 s80, 0x800
	s_movk_i32 s81, 0x2c00
	s_mov_b32 s82, 1
	s_movk_i32 s83, 0x1600
	s_mul_hi_u32 s84, s74, 0xba2e8c
	s_mul_i32 s75, s84, 0x160
	s_sub_u32 s85, s74, s75
	s_branch .Lp0_dd_a
.Lp0_m3_a:
	s_sub_u32 s74, s72, 0x4400
	s_add_u32 s76, s24, 0x5800000
	s_addc_u32 s77, s25, 0
	s_add_u32 s78, s30, 0x7300000
	s_addc_u32 s79, s31, 0
	s_movk_i32 s80, 0x800
	s_movk_i32 s81, 0x2c00
	s_mov_b32 s82, 1
	s_movk_i32 s83, 0x1600
	s_mul_hi_u32 s84, s74, 0xba2e8c
	s_mul_i32 s75, s84, 0x160
	s_sub_u32 s85, s74, s75
	s_branch .Lp0_dd_a
.Lp0_m4_a:
	s_sub_u32 s74, s72, 0x7000
	s_mov_b64 s[76:77], s[26:27]
	s_add_u32 s78, s30, 0x9f00000
	s_addc_u32 s79, s31, 0
	s_movk_i32 s80, 0x1600
	s_movk_i32 s81, 0x800
	s_mov_b32 s82, 0
	s_movk_i32 s83, 0x0
	s_lshr_b32 s84, s74, 6
	s_and_b32 s85, s74, 63
	s_branch .Lp0_dd_a
.Lp0_m5_a:
	s_sub_u32 s74, s72, 0x8600
	s_add_u32 s76, s26, 0x2c00000
	s_addc_u32 s77, s27, 0
	s_add_u32 s78, s30, 0xb500000
	s_addc_u32 s79, s31, 0
	s_movk_i32 s80, 0x1600
	s_movk_i32 s81, 0x800
	s_mov_b32 s82, 0
	s_movk_i32 s83, 0x0
	s_lshr_b32 s84, s74, 6
	s_and_b32 s85, s74, 63
	s_branch .Lp0_dd_a
.Lp0_m6_a:
	s_sub_u32 s74, s72, 0x9c00
	s_mov_b64 s[76:77], s[20:21]
	s_add_u32 s78, s30, 0xcb00000
	s_addc_u32 s79, s31, 0
	s_movk_i32 s80, 0x800
	s_movk_i32 s81, 0x1c50
	s_mov_b32 s82, 3
	s_movk_i32 s83, 0x0
	s_mul_hi_u32 s84, s74, 0x120b471
	s_mul_i32 s75, s84, 0xe3
	s_sub_u32 s85, s74, s75
.Lp0_dd_a:
	s_lshl_b32 s86, s85, 5
	s_lshl_b32 s87, s84, 6
	s_mul_i32 s75, s87, s81
	s_add_u32 s75, s75, s86
	s_lshl_b32 s75, s75, 2
	s_add_u32 s88, s76, s75
	s_addc_u32 s89, s77, 0
	s_lshl_b32 s90, s81, 3
	s_lshl_b32 s95, s81, 2
	v_mad_u32_u24 v141, v101, s95, v100
	s_mov_b32 s91, 0
	s_cmp_eq_u32 s82, 3
	s_cbranch_scc0 .Lp0_np_a
	s_cmp_eq_u32 s85, 0xe2
	s_cselect_b32 s91, 1, 0
.Lp0_np_a:
	s_cmp_eq_u32 s91, 1
	s_cbranch_scc0 .Lp0_fl_a
	s_mov_b32 exec_lo, 0xffff
	s_mov_b32 exec_hi, 0xffff
.Lp0_fl_a:
	global_load_dword v150, v141, s[88:89]
	s_add_u32 s88, s88, s90
	s_addc_u32 s89, s89, 0
	global_load_dword v151, v141, s[88:89]
	s_add_u32 s88, s88, s90
	s_addc_u32 s89, s89, 0
	global_load_dword v152, v141, s[88:89]
	s_add_u32 s88, s88, s90
	s_addc_u32 s89, s89, 0
	global_load_dword v153, v141, s[88:89]
	s_add_u32 s88, s88, s90
	s_addc_u32 s89, s89, 0
	global_load_dword v154, v141, s[88:89]
	s_add_u32 s88, s88, s90
	s_addc_u32 s89, s89, 0
	global_load_dword v155, v141, s[88:89]
	s_add_u32 s88, s88, s90
	s_addc_u32 s89, s89, 0
	global_load_dword v156, v141, s[88:89]
	s_add_u32 s88, s88, s90
	s_addc_u32 s89, s89, 0
	global_load_dword v157, v141, s[88:89]
	s_add_u32 s88, s88, s90
	s_addc_u32 s89, s89, 0
	global_load_dword v158, v141, s[88:89]
	s_add_u32 s88, s88, s90
	s_addc_u32 s89, s89, 0
	global_load_dword v159, v141, s[88:89]
	s_add_u32 s88, s88, s90
	s_addc_u32 s89, s89, 0
	global_load_dword v160, v141, s[88:89]
	s_add_u32 s88, s88, s90
	s_addc_u32 s89, s89, 0
	global_load_dword v161, v141, s[88:89]
	s_add_u32 s88, s88, s90
	s_addc_u32 s89, s89, 0
	global_load_dword v162, v141, s[88:89]
	s_add_u32 s88, s88, s90
	s_addc_u32 s89, s89, 0
	global_load_dword v163, v141, s[88:89]
	s_add_u32 s88, s88, s90
	s_addc_u32 s89, s89, 0
	global_load_dword v164, v141, s[88:89]
	s_add_u32 s88, s88, s90
	s_addc_u32 s89, s89, 0
	global_load_dword v165, v141, s[88:89]
	s_add_u32 s88, s88, s90
	s_addc_u32 s89, s89, 0
	global_load_dword v166, v141, s[88:89]
	s_add_u32 s88, s88, s90
	s_addc_u32 s89, s89, 0
	global_load_dword v167, v141, s[88:89]
	s_add_u32 s88, s88, s90
	s_addc_u32 s89, s89, 0
	global_load_dword v168, v141, s[88:89]
	s_add_u32 s88, s88, s90
	s_addc_u32 s89, s89, 0
	global_load_dword v169, v141, s[88:89]
	s_add_u32 s88, s88, s90
	s_addc_u32 s89, s89, 0
	global_load_dword v170, v141, s[88:89]
	s_add_u32 s88, s88, s90
	s_addc_u32 s89, s89, 0
	global_load_dword v171, v141, s[88:89]
	s_add_u32 s88, s88, s90
	s_addc_u32 s89, s89, 0
	global_load_dword v172, v141, s[88:89]
	s_add_u32 s88, s88, s90
	s_addc_u32 s89, s89, 0
	global_load_dword v173, v141, s[88:89]
	s_add_u32 s88, s88, s90
	s_addc_u32 s89, s89, 0
	global_load_dword v174, v141, s[88:89]
	s_add_u32 s88, s88, s90
	s_addc_u32 s89, s89, 0
	global_load_dword v175, v141, s[88:89]
	s_add_u32 s88, s88, s90
	s_addc_u32 s89, s89, 0
	global_load_dword v176, v141, s[88:89]
	s_add_u32 s88, s88, s90
	s_addc_u32 s89, s89, 0
	global_load_dword v177, v141, s[88:89]
	s_add_u32 s88, s88, s90
	s_addc_u32 s89, s89, 0
	global_load_dword v178, v141, s[88:89]
	s_add_u32 s88, s88, s90
	s_addc_u32 s89, s89, 0
	global_load_dword v179, v141, s[88:89]
	s_add_u32 s88, s88, s90
	s_addc_u32 s89, s89, 0
	global_load_dword v180, v141, s[88:89]
	s_add_u32 s88, s88, s90
	s_addc_u32 s89, s89, 0
	global_load_dword v181, v141, s[88:89]
	s_mov_b64 exec, -1
	s_lshl_b32 s95, s87, 1
	s_add_u32 s92, s78, s95
	s_addc_u32 s93, s79, 0
	s_mov_b32 s94, s91
	s_lshl_b32 s96, s80, 1
	v_mov_b32_e32 v142, s83
	s_cmp_eq_u32 s82, 0
	s_cbranch_scc1 .Lp0_r0_a
	s_cmp_eq_u32 s82, 1
	s_cbranch_scc1 .Lp0_r1_a
	s_cmp_lt_u32 s86, 0x1000
	s_cbranch_scc1 .Lp0_r3a_a
	s_cmp_lt_u32 s86, 0x1800
	s_cbranch_scc1 .Lp0_r0_a
	s_cmp_lt_u32 s86, 0x1c00
	s_cbranch_scc1 .Lp0_r3c_a
	s_add_u32 s95, s86, 0
	v_add_u32_e32 v143, s95, v105
	v_add_u32_e32 v200, 0xffffe3f0, v143
	v_and_b32_e32 v201, 32, v200
	v_lshlrev_b32_e32 v201, 2, v201
	v_and_b32_e32 v200, 31, v200
	v_add_u32_e32 v200, 0x1c00, v200
	v_add_u32_e32 v200, v200, v201
	v_mov_b32_e32 v202, 0x1c10
	v_cmp_gt_u32_e32 vcc, v202, v143
	v_add_u32_e32 v201, 32, v143
	s_nop 0
	v_cndmask_b32_e32 v203, v200, v201, vcc
	v_mad_u32_u24 v108, v203, s96, v104
	s_add_u32 s95, s86, 8
	v_add_u32_e32 v143, s95, v105
	v_add_u32_e32 v200, 0xffffe3f0, v143
	v_and_b32_e32 v201, 32, v200
	v_lshlrev_b32_e32 v201, 2, v201
	v_and_b32_e32 v200, 31, v200
	v_add_u32_e32 v200, 0x1c00, v200
	v_add_u32_e32 v200, v200, v201
	v_mov_b32_e32 v202, 0x1c10
	v_cmp_gt_u32_e32 vcc, v202, v143
	v_add_u32_e32 v201, 32, v143
	s_nop 0
	v_cndmask_b32_e32 v203, v200, v201, vcc
	v_mad_u32_u24 v109, v203, s96, v104
	s_add_u32 s95, s86, 16
	v_add_u32_e32 v143, s95, v105
	v_add_u32_e32 v200, 0xffffe3f0, v143
	v_and_b32_e32 v201, 32, v200
	v_lshlrev_b32_e32 v201, 2, v201
	v_and_b32_e32 v200, 31, v200
	v_add_u32_e32 v200, 0x1c00, v200
	v_add_u32_e32 v200, v200, v201
	v_mov_b32_e32 v202, 0x1c10
	v_cmp_gt_u32_e32 vcc, v202, v143
	v_add_u32_e32 v201, 32, v143
	s_nop 0
	v_cndmask_b32_e32 v203, v200, v201, vcc
	v_mad_u32_u24 v110, v203, s96, v104
	s_add_u32 s95, s86, 24
	v_add_u32_e32 v143, s95, v105
	v_add_u32_e32 v200, 0xffffe3f0, v143
	v_and_b32_e32 v201, 32, v200
	v_lshlrev_b32_e32 v201, 2, v201
	v_and_b32_e32 v200, 31, v200
	v_add_u32_e32 v200, 0x1c00, v200
	v_add_u32_e32 v200, v200, v201
	v_mov_b32_e32 v202, 0x1c10
	v_cmp_gt_u32_e32 vcc, v202, v143
	v_add_u32_e32 v201, 32, v143
	s_nop 0
	v_cndmask_b32_e32 v203, v200, v201, vcc
	v_mad_u32_u24 v140, v203, s96, v104
	s_branch .Lp0_rd_a
.Lp0_r3c_a:
	s_add_u32 s95, s86, 0
	v_add_u32_e32 v143, s95, v105
	v_and_b32_e32 v200, 0xc0, v143
	v_lshrrev_b32_e32 v200, 1, v200
	v_and_b32_e32 v201, 32, v143
	v_lshlrev_b32_e32 v201, 2, v201
	v_and_b32_e32 v202, 0xffffff1f, v143
	v_or3_b32 v203, v202, v200, v201
	v_mad_u32_u24 v108, v203, s96, v104
	s_add_u32 s95, s86, 8
	v_add_u32_e32 v143, s95, v105
	v_and_b32_e32 v200, 0xc0, v143
	v_lshrrev_b32_e32 v200, 1, v200
	v_and_b32_e32 v201, 32, v143
	v_lshlrev_b32_e32 v201, 2, v201
	v_and_b32_e32 v202, 0xffffff1f, v143
	v_or3_b32 v203, v202, v200, v201
	v_mad_u32_u24 v109, v203, s96, v104
	s_add_u32 s95, s86, 16
	v_add_u32_e32 v143, s95, v105
	v_and_b32_e32 v200, 0xc0, v143
	v_lshrrev_b32_e32 v200, 1, v200
	v_and_b32_e32 v201, 32, v143
	v_lshlrev_b32_e32 v201, 2, v201
	v_and_b32_e32 v202, 0xffffff1f, v143
	v_or3_b32 v203, v202, v200, v201
	v_mad_u32_u24 v110, v203, s96, v104
	s_add_u32 s95, s86, 24
	v_add_u32_e32 v143, s95, v105
	v_and_b32_e32 v200, 0xc0, v143
	v_lshrrev_b32_e32 v200, 1, v200
	v_and_b32_e32 v201, 32, v143
	v_lshlrev_b32_e32 v201, 2, v201
	v_and_b32_e32 v202, 0xffffff1f, v143
	v_or3_b32 v203, v202, v200, v201
	v_mad_u32_u24 v140, v203, s96, v104
	s_branch .Lp0_rd_a
.Lp0_r3a_a:
	s_add_u32 s95, s86, 0
	v_add_u32_e32 v143, s95, v105
	v_and_b32_e32 v200, 64, v143
	v_lshlrev_b32_e32 v200, 1, v200
	v_lshrrev_b32_e32 v201, 1, v143
	v_and_b32_e32 v201, 64, v201
	v_and_b32_e32 v202, 0xffffff3f, v143
	v_or3_b32 v203, v202, v200, v201
	v_mad_u32_u24 v108, v203, s96, v104
	s_add_u32 s95, s86, 8
	v_add_u32_e32 v143, s95, v105
	v_and_b32_e32 v200, 64, v143
	v_lshlrev_b32_e32 v200, 1, v200
	v_lshrrev_b32_e32 v201, 1, v143
	v_and_b32_e32 v201, 64, v201
	v_and_b32_e32 v202, 0xffffff3f, v143
	v_or3_b32 v203, v202, v200, v201
	v_mad_u32_u24 v109, v203, s96, v104
	s_add_u32 s95, s86, 16
	v_add_u32_e32 v143, s95, v105
	v_and_b32_e32 v200, 64, v143
	v_lshlrev_b32_e32 v200, 1, v200
	v_lshrrev_b32_e32 v201, 1, v143
	v_and_b32_e32 v201, 64, v201
	v_and_b32_e32 v202, 0xffffff3f, v143
	v_or3_b32 v203, v202, v200, v201
	v_mad_u32_u24 v110, v203, s96, v104
	s_add_u32 s95, s86, 24
	v_add_u32_e32 v143, s95, v105
	v_and_b32_e32 v200, 64, v143
	v_lshlrev_b32_e32 v200, 1, v200
	v_lshrrev_b32_e32 v201, 1, v143
	v_and_b32_e32 v201, 64, v201
	v_and_b32_e32 v202, 0xffffff3f, v143
	v_or3_b32 v203, v202, v200, v201
	v_mad_u32_u24 v140, v203, s96, v104
	s_branch .Lp0_rd_a
.Lp0_r1_a:
	s_add_u32 s95, s86, 0
	v_add_u32_e32 v143, s95, v105
	v_cmp_le_u32_e32 vcc, v142, v143
	s_nop 1
	v_cndmask_b32_e32 v200, 0, v142, vcc
	v_cndmask_b32_e32 v201, 0, v106, vcc
	v_sub_u32_e32 v200, v143, v200
	v_and_b32_e32 v202, 0xffffff80, v200
	v_add3_u32 v203, v200, v202, v201
	v_mad_u32_u24 v108, v203, s96, v104
	s_add_u32 s95, s86, 8
	v_add_u32_e32 v143, s95, v105
	v_cmp_le_u32_e32 vcc, v142, v143
	s_nop 1
	v_cndmask_b32_e32 v200, 0, v142, vcc
	v_cndmask_b32_e32 v201, 0, v106, vcc
	v_sub_u32_e32 v200, v143, v200
	v_and_b32_e32 v202, 0xffffff80, v200
	v_add3_u32 v203, v200, v202, v201
	v_mad_u32_u24 v109, v203, s96, v104
	s_add_u32 s95, s86, 16
	v_add_u32_e32 v143, s95, v105
	v_cmp_le_u32_e32 vcc, v142, v143
	s_nop 1
	v_cndmask_b32_e32 v200, 0, v142, vcc
	v_cndmask_b32_e32 v201, 0, v106, vcc
	v_sub_u32_e32 v200, v143, v200
	v_and_b32_e32 v202, 0xffffff80, v200
	v_add3_u32 v203, v200, v202, v201
	v_mad_u32_u24 v110, v203, s96, v104
	s_add_u32 s95, s86, 24
	v_add_u32_e32 v143, s95, v105
	v_cmp_le_u32_e32 vcc, v142, v143
	s_nop 1
	v_cndmask_b32_e32 v200, 0, v142, vcc
	v_cndmask_b32_e32 v201, 0, v106, vcc
	v_sub_u32_e32 v200, v143, v200
	v_and_b32_e32 v202, 0xffffff80, v200
	v_add3_u32 v203, v200, v202, v201
	v_mad_u32_u24 v140, v203, s96, v104
	s_branch .Lp0_rd_a
.Lp0_r0_a:
	s_add_u32 s95, s86, 0
	v_add_u32_e32 v143, s95, v105
	v_mad_u32_u24 v108, v143, s96, v104
	s_add_u32 s95, s86, 8
	v_add_u32_e32 v143, s95, v105
	v_mad_u32_u24 v109, v143, s96, v104
	s_add_u32 s95, s86, 16
	v_add_u32_e32 v143, s95, v105
	v_mad_u32_u24 v110, v143, s96, v104
	s_add_u32 s95, s86, 24
	v_add_u32_e32 v143, s95, v105
	v_mad_u32_u24 v140, v143, s96, v104

.Lp0_loop:
	ds_write_b32 v102, v150
	ds_write_b32 v102, v151 offset:264
	ds_write_b32 v102, v152 offset:528
	ds_write_b32 v102, v153 offset:792
	ds_write_b32 v102, v154 offset:1056
	ds_write_b32 v102, v155 offset:1320
	ds_write_b32 v102, v156 offset:1584
	ds_write_b32 v102, v157 offset:1848
	ds_write_b32 v102, v158 offset:2112
	ds_write_b32 v102, v159 offset:2376
	ds_write_b32 v102, v160 offset:2640
	ds_write_b32 v102, v161 offset:2904
	ds_write_b32 v102, v162 offset:3168
	ds_write_b32 v102, v163 offset:3432
	ds_write_b32 v102, v164 offset:3696
	ds_write_b32 v102, v165 offset:3960
	ds_write_b32 v102, v166 offset:4224
	ds_write_b32 v102, v167 offset:4488
	ds_write_b32 v102, v168 offset:4752
	ds_write_b32 v102, v169 offset:5016
	ds_write_b32 v102, v170 offset:5280
	ds_write_b32 v102, v171 offset:5544
	ds_write_b32 v102, v172 offset:5808
	ds_write_b32 v102, v173 offset:6072
	ds_write_b32 v102, v174 offset:6336
	ds_write_b32 v102, v175 offset:6600
	ds_write_b32 v102, v176 offset:6864
	ds_write_b32 v102, v177 offset:7128
	ds_write_b32 v102, v178 offset:7392
	ds_write_b32 v102, v179 offset:7656
	ds_write_b32 v102, v180 offset:7920
	ds_write_b32 v102, v181 offset:8184
	s_add_u32 s72, s72, 0x800
	s_sub_u32 s73, s73, 1
	s_cmp_eq_u32 s73, 0
	s_cbranch_scc1 .Lp0_nold
	s_cmp_lt_u32 s72, 0x800
	s_cbranch_scc1 .Lp0_m0_b
	s_cmp_lt_u32 s72, 0x1800
	s_cbranch_scc1 .Lp0_m1_b
	s_cmp_lt_u32 s72, 0x4400
	s_cbranch_scc1 .Lp0_m2_b
	s_cmp_lt_u32 s72, 0x7000
	s_cbranch_scc1 .Lp0_m3_b
	s_cmp_lt_u32 s72, 0x8600
	s_cbranch_scc1 .Lp0_m4_b
	s_cmp_lt_u32 s72, 0x9c00
	s_cbranch_scc1 .Lp0_m5_b
	s_cmp_lt_u32 s72, 0xb860
	s_cbranch_scc1 .Lp0_m6_b
	s_sub_u32 s74, s72, 0xb860
	s_mov_b64 s[76:77], s[22:23]
	s_add_u32 s78, s30, 0xe800000
	s_addc_u32 s79, s31, 0
	s_movk_i32 s80, 0x800
	s_movk_i32 s81, 0x800
	s_mov_b32 s82, 0
	s_movk_i32 s83, 0x0
	s_lshr_b32 s84, s74, 6
	s_and_b32 s85, s74, 63
	s_branch .Lp0_dd_b

.Lp0_fl_b:
	global_load_dword v150, v141, s[88:89]
	s_add_u32 s88, s88, s90
	s_addc_u32 s89, s89, 0
	global_load_dword v151, v141, s[88:89]
	s_add_u32 s88, s88, s90
	s_addc_u32 s89, s89, 0
	global_load_dword v152, v141, s[88:89]
	s_add_u32 s88, s88, s90
	s_addc_u32 s89, s89, 0
	global_load_dword v153, v141, s[88:89]
	s_add_u32 s88, s88, s90
	s_addc_u32 s89, s89, 0
	global_load_dword v154, v141, s[88:89]
	s_add_u32 s88, s88, s90
	s_addc_u32 s89, s89, 0
	global_load_dword v155, v141, s[88:89]
	s_add_u32 s88, s88, s90
	s_addc_u32 s89, s89, 0
	global_load_dword v156, v141, s[88:89]
	s_add_u32 s88, s88, s90
	s_addc_u32 s89, s89, 0
	global_load_dword v157, v141, s[88:89]
	s_add_u32 s88, s88, s90
	s_addc_u32 s89, s89, 0
	global_load_dword v158, v141, s[88:89]
	s_add_u32 s88, s88, s90
	s_addc_u32 s89, s89, 0
	global_load_dword v159, v141, s[88:89]
	s_add_u32 s88, s88, s90
	s_addc_u32 s89, s89, 0
	global_load_dword v160, v141, s[88:89]
	s_add_u32 s88, s88, s90
	s_addc_u32 s89, s89, 0
	global_load_dword v161, v141, s[88:89]
	s_add_u32 s88, s88, s90
	s_addc_u32 s89, s89, 0
	global_load_dword v162, v141, s[88:89]
	s_add_u32 s88, s88, s90
	s_addc_u32 s89, s89, 0
	global_load_dword v163, v141, s[88:89]
	s_add_u32 s88, s88, s90
	s_addc_u32 s89, s89, 0
	global_load_dword v164, v141, s[88:89]
	s_add_u32 s88, s88, s90
	s_addc_u32 s89, s89, 0
	global_load_dword v165, v141, s[88:89]
	s_add_u32 s88, s88, s90
	s_addc_u32 s89, s89, 0
	global_load_dword v166, v141, s[88:89]
	s_add_u32 s88, s88, s90
	s_addc_u32 s89, s89, 0
	global_load_dword v167, v141, s[88:89]
	s_add_u32 s88, s88, s90
	s_addc_u32 s89, s89, 0
	global_load_dword v168, v141, s[88:89]
	s_add_u32 s88, s88, s90
	s_addc_u32 s89, s89, 0
	global_load_dword v169, v141, s[88:89]
	s_add_u32 s88, s88, s90
	s_addc_u32 s89, s89, 0
	global_load_dword v170, v141, s[88:89]
	s_add_u32 s88, s88, s90
	s_addc_u32 s89, s89, 0
	global_load_dword v171, v141, s[88:89]
	s_add_u32 s88, s88, s90
	s_addc_u32 s89, s89, 0
	global_load_dword v172, v141, s[88:89]
	s_add_u32 s88, s88, s90
	s_addc_u32 s89, s89, 0
	global_load_dword v173, v141, s[88:89]
	s_add_u32 s88, s88, s90
	s_addc_u32 s89, s89, 0
	global_load_dword v174, v141, s[88:89]
	s_add_u32 s88, s88, s90
	s_addc_u32 s89, s89, 0
	global_load_dword v175, v141, s[88:89]
	s_add_u32 s88, s88, s90
	s_addc_u32 s89, s89, 0
	global_load_dword v176, v141, s[88:89]
	s_add_u32 s88, s88, s90
	s_addc_u32 s89, s89, 0
	global_load_dword v177, v141, s[88:89]
	s_add_u32 s88, s88, s90
	s_addc_u32 s89, s89, 0
	global_load_dword v178, v141, s[88:89]
	s_add_u32 s88, s88, s90
	s_addc_u32 s89, s89, 0
	global_load_dword v179, v141, s[88:89]
	s_add_u32 s88, s88, s90
	s_addc_u32 s89, s89, 0
	global_load_dword v180, v141, s[88:89]
	s_add_u32 s88, s88, s90
	s_addc_u32 s89, s89, 0
	global_load_dword v181, v141, s[88:89]
	s_mov_b64 exec, -1
.Lp0_nold:
	s_waitcnt lgkmcnt(0)
	ds_read2_b32 v[66:67], v103 offset1:33
	ds_read2_b32 v[68:69], v103 offset0:66 offset1:99
	ds_read2_b32 v[70:71], v103 offset0:132 offset1:165
	ds_read2_b32 v[72:73], v103 offset0:198 offset1:231
	ds_read2_b32 v[74:75], v103 offset0:8 offset1:41
	ds_read2_b32 v[76:77], v103 offset0:74 offset1:107
	ds_read2_b32 v[78:79], v103 offset0:140 offset1:173
	ds_read2_b32 v[80:81], v103 offset0:206 offset1:239
	ds_read2_b32 v[82:83], v103 offset0:16 offset1:49
	ds_read2_b32 v[84:85], v103 offset0:82 offset1:115
	ds_read2_b32 v[86:87], v103 offset0:148 offset1:181
	ds_read2_b32 v[88:89], v103 offset0:214 offset1:247
	ds_read2_b32 v[90:91], v103 offset0:24 offset1:57
	ds_read2_b32 v[94:95], v103 offset0:90 offset1:123
	ds_read2_b32 v[96:97], v103 offset0:156 offset1:189
	ds_read2_b32 v[98:99], v103 offset0:222 offset1:255
	s_waitcnt lgkmcnt(12)
	v_cvt_pk_bf16_f32 v184, v66, v67
	v_cvt_pk_bf16_f32 v185, v68, v69
	v_cvt_pk_bf16_f32 v186, v70, v71
	v_cvt_pk_bf16_f32 v187, v72, v73
	global_store_dwordx4 v108, v[184:187], s[92:93]
	s_waitcnt lgkmcnt(8)
	v_cvt_pk_bf16_f32 v188, v74, v75
	v_cvt_pk_bf16_f32 v189, v76, v77
	v_cvt_pk_bf16_f32 v190, v78, v79
	v_cvt_pk_bf16_f32 v191, v80, v81
	global_store_dwordx4 v109, v[188:191], s[92:93]
	s_waitcnt lgkmcnt(4)
	v_cvt_pk_bf16_f32 v192, v82, v83
	v_cvt_pk_bf16_f32 v193, v84, v85
	v_cvt_pk_bf16_f32 v194, v86, v87
	v_cvt_pk_bf16_f32 v195, v88, v89
	s_cmp_eq_u32 s94, 1
	s_cbranch_scc1 .Lp0_nost2
	global_store_dwordx4 v110, v[192:195], s[92:93]
.Lp0_nost2:
	s_waitcnt lgkmcnt(0)
	v_cvt_pk_bf16_f32 v196, v90, v91
	v_cvt_pk_bf16_f32 v197, v94, v95
	v_cvt_pk_bf16_f32 v198, v96, v97
	v_cvt_pk_bf16_f32 v199, v98, v99
	s_cmp_eq_u32 s94, 1
	s_cbranch_scc1 .Lp0_nost3
	global_store_dwordx4 v140, v[196:199], s[92:93]
.Lp0_nost3:
	s_cmp_eq_u32 s73, 0
	s_cbranch_scc1 .Lp0_done
	s_mov_b32 s97, s94
	s_lshl_b32 s95, s87, 1
	s_add_u32 s92, s78, s95
	s_addc_u32 s93, s79, 0
	s_mov_b32 s94, s91
	s_lshl_b32 s96, s80, 1
	v_mov_b32_e32 v142, s83
	s_cmp_eq_u32 s82, 0
	s_cbranch_scc1 .Lp0_r0_b
	s_cmp_eq_u32 s82, 1
	s_cbranch_scc1 .Lp0_r1_b
	s_cmp_lt_u32 s86, 0x1000
	s_cbranch_scc1 .Lp0_r3a_b
	s_cmp_lt_u32 s86, 0x1800
	s_cbranch_scc1 .Lp0_r0_b
	s_cmp_lt_u32 s86, 0x1c00
	s_cbranch_scc1 .Lp0_r3c_b
	s_add_u32 s95, s86, 0
	v_add_u32_e32 v143, s95, v105
	v_add_u32_e32 v200, 0xffffe3f0, v143
	v_and_b32_e32 v201, 32, v200
	v_lshlrev_b32_e32 v201, 2, v201
	v_and_b32_e32 v200, 31, v200
	v_add_u32_e32 v200, 0x1c00, v200
	v_add_u32_e32 v200, v200, v201
	v_mov_b32_e32 v202, 0x1c10
	v_cmp_gt_u32_e32 vcc, v202, v143
	v_add_u32_e32 v201, 32, v143
	s_nop 0
	v_cndmask_b32_e32 v203, v200, v201, vcc
	v_mad_u32_u24 v108, v203, s96, v104
	s_add_u32 s95, s86, 8
	v_add_u32_e32 v143, s95, v105
	v_add_u32_e32 v200, 0xffffe3f0, v143
	v_and_b32_e32 v201, 32, v200
	v_lshlrev_b32_e32 v201, 2, v201
	v_and_b32_e32 v200, 31, v200
	v_add_u32_e32 v200, 0x1c00, v200
	v_add_u32_e32 v200, v200, v201
	v_mov_b32_e32 v202, 0x1c10
	v_cmp_gt_u32_e32 vcc, v202, v143
	v_add_u32_e32 v201, 32, v143
	s_nop 0
	v_cndmask_b32_e32 v203, v200, v201, vcc
	v_mad_u32_u24 v109, v203, s96, v104
	s_add_u32 s95, s86, 16
	v_add_u32_e32 v143, s95, v105
	v_add_u32_e32 v200, 0xffffe3f0, v143
	v_and_b32_e32 v201, 32, v200
	v_lshlrev_b32_e32 v201, 2, v201
	v_and_b32_e32 v200, 31, v200
	v_add_u32_e32 v200, 0x1c00, v200
	v_add_u32_e32 v200, v200, v201
	v_mov_b32_e32 v202, 0x1c10
	v_cmp_gt_u32_e32 vcc, v202, v143
	v_add_u32_e32 v201, 32, v143
	s_nop 0
	v_cndmask_b32_e32 v203, v200, v201, vcc
	v_mad_u32_u24 v110, v203, s96, v104
	s_add_u32 s95, s86, 24
	v_add_u32_e32 v143, s95, v105
	v_add_u32_e32 v200, 0xffffe3f0, v143
	v_and_b32_e32 v201, 32, v200
	v_lshlrev_b32_e32 v201, 2, v201
	v_and_b32_e32 v200, 31, v200
	v_add_u32_e32 v200, 0x1c00, v200
	v_add_u32_e32 v200, v200, v201
	v_mov_b32_e32 v202, 0x1c10
	v_cmp_gt_u32_e32 vcc, v202, v143
	v_add_u32_e32 v201, 32, v143
	s_nop 0
	v_cndmask_b32_e32 v203, v200, v201, vcc
	v_mad_u32_u24 v140, v203, s96, v104
	s_branch .Lp0_rd_b

.Lp0_rd_b:
	s_cmp_eq_u32 s97, 1
	s_cbranch_scc1 .Lp0_w2
	s_waitcnt vmcnt(4)
	s_branch .Lp0_loop
.Lp0_w2:
	s_waitcnt vmcnt(2)
	s_branch .Lp0_loop
.Lp0_done:
	v_add_u32_e32 v20, 0xc000, v20
.Lp0_skip:
	s_mov_b32 s0, 0xc160
	v_cmp_gt_i32_e32 vcc, s0, v20
	s_and_saveexec_b64 s[4:5], vcc
	s_cbranch_execz .LBB0_304
	v_lshlrev_b32_e32 v0, 1, v144
	v_and_b32_e32 v2, 62, v0
	s_mov_b32 s0, 0x3c800000
	v_cvt_f32_ubyte0_e32 v1, v0
	v_cvt_f32_ubyte0_e32 v0, v2
	s_brev_b32 s1, 60
	v_pk_mul_f32 v[0:1], v[0:1], s[0:1]
	v_mov_b32_e32 v7, 0x461c4000
	v_cmp_eq_f32_e32 vcc, 0, v1
	s_mov_b32 s0, 0x3f2aaaab
	v_mov_b32_e32 v21, 0x3e91f4c4
	v_cndmask_b32_e64 v14, v7, 1.0, vcc
	v_frexp_mant_f32_e32 v2, v14
	v_cmp_gt_f32_e32 vcc, s0, v2
	s_mov_b32 s1, 0x3f317218
	v_mov_b32_e32 v22, 0x3ecccdef
	v_cndmask_b32_e64 v3, 1.0, 2.0, vcc
	v_mul_f32_e32 v2, v2, v3
	v_add_f32_e32 v5, 1.0, v2
	v_rcp_f32_e32 v12, v5
	v_add_f32_e32 v3, -1.0, v5
	v_sub_f32_e32 v9, v2, v3
	v_add_f32_e32 v3, -1.0, v2
	v_mul_f32_e32 v13, v3, v12
	v_mul_f32_e32 v4, v5, v13
	v_fma_f32 v8, v13, v5, -v4
	v_fmac_f32_e32 v8, v13, v9
	v_add_f32_e32 v2, v4, v8
	v_sub_f32_e32 v5, v3, v2
	v_pk_add_f32 v[10:11], v[2:3], v[4:5] neg_lo:[0,1] neg_hi:[0,1]
	v_mov_b32_e32 v9, v2
	v_pk_add_f32 v[2:3], v[10:11], v[8:9] neg_lo:[0,1] neg_hi:[0,1]
	s_mov_b32 s7, 0x42b17218
	v_add_f32_e32 v2, v2, v3
	v_add_f32_e32 v2, v5, v2
	v_mul_f32_e32 v3, v12, v2
	v_add_f32_e32 v2, v13, v3
	v_sub_f32_e32 v4, v2, v13
	v_sub_f32_e32 v15, v3, v4
	v_mul_f32_e32 v3, v2, v2
	v_fma_f32 v5, v2, v2, -v3
	v_add_f32_e32 v4, v15, v15
	v_fmac_f32_e32 v5, v2, v4
	v_add_f32_e32 v4, v3, v5
	v_fmamk_f32 v8, v4, 0x3e76c4e1, v21
	v_fmaak_f32 v8, v4, v8, 0x3ecccdef
	v_sub_f32_e32 v3, v4, v3
	v_sub_f32_e32 v16, v5, v3
	v_mul_f32_e32 v3, v4, v8
	v_fma_f32 v5, v4, v8, -v3
	v_fmac_f32_e32 v5, v16, v8
	v_add_f32_e32 v8, v3, v5
	v_add_f32_e32 v9, 0x3f2aaaaa, v8
	v_sub_f32_e32 v3, v8, v3
	v_sub_f32_e32 v3, v5, v3
	v_add_f32_e32 v5, 0xbf2aaaaa, v9
	v_add_f32_e32 v3, 0x31739010, v3
	v_sub_f32_e32 v5, v8, v5
	v_pk_mul_f32 v[10:11], v[2:3], v[4:5]
	v_pk_add_f32 v[12:13], v[2:3], v[4:5]
	v_fma_f32 v8, v4, v2, -v10
	v_fmac_f32_e32 v8, v4, v15
	v_mov_b32_e32 v11, v13
	v_fmac_f32_e32 v8, v16, v2
	v_pk_add_f32 v[4:5], v[10:11], v[8:9]
	v_ldexp_f32 v16, v15, 1
	v_sub_f32_e32 v3, v4, v10
	v_sub_f32_e32 v3, v8, v3
	v_sub_f32_e32 v8, v9, v5
	v_add_f32_e32 v11, v13, v8
	v_pk_mul_f32 v[8:9], v[4:5], v[4:5] op_sel:[0,1] op_sel_hi:[1,0]
	v_cvt_f64_f32_e32 v[12:13], v14
	v_frexp_exp_i32_f64_e32 v9, v[12:13]
	v_subbrev_co_u32_e32 v9, vcc, 0, v9, vcc
	v_cvt_f32_i32_e32 v9, v9
	v_fma_f32 v10, v4, v5, -v8
	v_fmac_f32_e32 v10, v4, v11
	v_fmac_f32_e32 v10, v3, v5
	v_mul_f32_e32 v4, 0x3f317218, v9
	v_fma_f32 v12, v9, s1, -v4
	v_fmac_f32_e32 v12, 0xb102e308, v9
	v_ldexp_f32 v13, v2, 1
	v_add_f32_e32 v5, v8, v10
	v_pk_add_f32 v[2:3], v[4:5], v[12:13]
	v_mov_b32_e32 v14, v5
	v_mov_b32_e32 v15, v3
	v_mov_b32_e32 v9, v13
	v_pk_add_f32 v[8:9], v[14:15], v[8:9] neg_lo:[0,1] neg_hi:[0,1]
	v_mov_b32_e32 v11, v5
	v_pk_add_f32 v[8:9], v[10:11], v[8:9] neg_lo:[0,1] neg_hi:[0,1]
	v_mov_b32_e32 v13, v2
	v_add_f32_e32 v5, v16, v8
	v_add_f32_e32 v5, v5, v9
	v_pk_add_f32 v[8:9], v[2:3], v[4:5] neg_lo:[0,1] neg_hi:[0,1]
	v_pk_add_f32 v[10:11], v[2:3], v[4:5]
	v_mov_b32_e32 v4, v5
	v_mov_b32_e32 v9, v11
	v_pk_add_f32 v[14:15], v[12:13], v[8:9] neg_lo:[0,1] neg_hi:[0,1]
	v_pk_add_f32 v[8:9], v[12:13], v[8:9]
	v_mov_b32_e32 v5, v2
	v_pk_add_f32 v[12:13], v[8:9], v[2:3] op_sel:[1,0] op_sel_hi:[0,1] neg_lo:[0,1] neg_hi:[0,1]
	v_pk_add_f32 v[16:17], v[10:11], v[12:13] op_sel_hi:[1,0] neg_lo:[0,1] neg_hi:[0,1]
	v_mov_b32_e32 v8, v11
	v_pk_mov_b32 v[10:11], v[2:3], v[12:13] op_sel:[1,0]
	v_mov_b32_e32 v16, v14
	v_pk_add_f32 v[10:11], v[8:9], v[10:11] neg_lo:[0,1] neg_hi:[0,1]
	v_cmp_eq_f32_e32 vcc, 0, v0
	v_pk_add_f32 v[2:3], v[4:5], v[10:11] neg_lo:[0,1] neg_hi:[0,1]
	v_mov_b32_e32 v15, v9
	v_pk_add_f32 v[4:5], v[16:17], v[2:3]
	v_cndmask_b32_e64 v3, v7, 1.0, vcc
	v_frexp_mant_f32_e32 v7, v3
	v_cmp_gt_f32_e32 vcc, s0, v7
	s_mov_b32 s8, 0x3fb8aa3b
	s_mov_b32 s6, 0x7f800000
	v_cndmask_b32_e64 v8, 1.0, 2.0, vcc
	v_mul_f32_e32 v7, v7, v8
	v_add_f32_e32 v8, 1.0, v7
	v_rcp_f32_e32 v23, v8
	v_add_f32_e32 v10, -1.0, v8
	v_add_f32_e32 v11, -1.0, v7
	v_sub_f32_e32 v10, v7, v10
	v_mul_f32_e32 v7, v11, v23
	v_mul_f32_e32 v12, v8, v7
	v_fma_f32 v16, v7, v8, -v12
	v_fmac_f32_e32 v16, v7, v10
	v_add_f32_e32 v10, v12, v16
	v_sub_f32_e32 v13, v11, v10
	v_pk_add_f32 v[18:19], v[10:11], v[12:13] neg_lo:[0,1] neg_hi:[0,1]
	v_mov_b32_e32 v17, v10
	v_pk_add_f32 v[10:11], v[18:19], v[16:17] neg_lo:[0,1] neg_hi:[0,1]
	s_mov_b32 s9, 0xc2ce8ed0
	v_add_f32_e32 v8, v10, v11
	v_add_f32_e32 v8, v13, v8
	v_mul_f32_e32 v8, v23, v8
	v_add_f32_e32 v10, v7, v8
	v_sub_f32_e32 v7, v10, v7
	v_sub_f32_e32 v7, v8, v7
	v_mul_f32_e32 v8, v10, v10
	v_fma_f32 v11, v10, v10, -v8
	v_add_f32_e32 v12, v7, v7
	v_fmac_f32_e32 v11, v10, v12
	v_add_f32_e32 v12, v8, v11
	v_fmac_f32_e32 v21, 0x3e76c4e1, v12
	v_fmac_f32_e32 v22, v12, v21
	v_sub_f32_e32 v8, v12, v8
	v_sub_f32_e32 v8, v11, v8
	v_mul_f32_e32 v11, v12, v22
	v_fma_f32 v13, v12, v22, -v11
	v_fmac_f32_e32 v13, v8, v22
	v_add_f32_e32 v16, v11, v13
	v_add_f32_e32 v17, 0x3f2aaaaa, v16
	v_sub_f32_e32 v11, v16, v11
	v_sub_f32_e32 v11, v13, v11
	v_add_f32_e32 v13, 0xbf2aaaaa, v17
	v_add_f32_e32 v11, 0x31739010, v11
	v_sub_f32_e32 v13, v16, v13
	v_pk_mul_f32 v[18:19], v[10:11], v[12:13]
	v_pk_add_f32 v[22:23], v[10:11], v[12:13]
	v_fma_f32 v16, v12, v10, -v18
	v_fmac_f32_e32 v16, v12, v7
	v_mov_b32_e32 v19, v23
	v_fmac_f32_e32 v16, v8, v10
	v_pk_add_f32 v[12:13], v[18:19], v[16:17]
	s_movk_i32 s10, 0x204
	v_sub_f32_e32 v8, v12, v18
	v_cvt_f64_f32_e32 v[18:19], v3
	v_frexp_exp_i32_f64_e32 v3, v[18:19]
	v_subbrev_co_u32_e32 v3, vcc, 0, v3, vcc
	v_cvt_f32_i32_e32 v3, v3
	v_sub_f32_e32 v8, v16, v8
	v_sub_f32_e32 v11, v17, v13
	v_pk_mul_f32 v[16:17], v[12:13], v[12:13] op_sel:[0,1] op_sel_hi:[1,0]
	v_add_f32_e32 v11, v23, v11
	v_fma_f32 v18, v12, v13, -v16
	v_fmac_f32_e32 v18, v12, v11
	v_mul_f32_e32 v12, 0x3f317218, v3
	v_fmac_f32_e32 v18, v8, v13
	v_fma_f32 v22, v3, s1, -v12
	v_fmac_f32_e32 v22, 0xb102e308, v3
	v_ldexp_f32 v23, v10, 1
	v_add_f32_e32 v13, v16, v18
	v_pk_add_f32 v[10:11], v[12:13], v[22:23]
	v_mov_b32_e32 v24, v13
	v_mov_b32_e32 v25, v11
	v_mov_b32_e32 v17, v23
	v_pk_add_f32 v[16:17], v[24:25], v[16:17] neg_lo:[0,1] neg_hi:[0,1]
	v_mov_b32_e32 v19, v13
	v_ldexp_f32 v3, v7, 1
	v_pk_add_f32 v[16:17], v[18:19], v[16:17] neg_lo:[0,1] neg_hi:[0,1]
	v_mov_b32_e32 v23, v10
	v_add_f32_e32 v3, v3, v16
	v_add_f32_e32 v13, v3, v17
	v_pk_add_f32 v[16:17], v[10:11], v[12:13] neg_lo:[0,1] neg_hi:[0,1]
	v_pk_add_f32 v[18:19], v[10:11], v[12:13]
	v_mov_b32_e32 v12, v13
	v_mov_b32_e32 v17, v19
	v_pk_add_f32 v[24:25], v[22:23], v[16:17] neg_lo:[0,1] neg_hi:[0,1]
	v_pk_add_f32 v[16:17], v[22:23], v[16:17]
	v_mov_b32_e32 v13, v10
	v_pk_add_f32 v[22:23], v[16:17], v[10:11] op_sel:[1,0] op_sel_hi:[0,1] neg_lo:[0,1] neg_hi:[0,1]
	v_pk_add_f32 v[26:27], v[18:19], v[22:23] op_sel_hi:[1,0] neg_lo:[0,1] neg_hi:[0,1]
	v_mov_b32_e32 v16, v19
	v_pk_mov_b32 v[18:19], v[10:11], v[22:23] op_sel:[1,0]
	v_mov_b32_e32 v26, v24
	v_pk_add_f32 v[18:19], v[16:17], v[18:19] neg_lo:[0,1] neg_hi:[0,1]
	v_mov_b32_e32 v23, v5
	v_pk_add_f32 v[10:11], v[12:13], v[18:19] neg_lo:[0,1] neg_hi:[0,1]
	v_mov_b32_e32 v19, v4
	v_pk_add_f32 v[12:13], v[26:27], v[10:11]
	v_mov_b32_e32 v8, v17
	v_mov_b32_e32 v18, v12
	v_mov_b32_e32 v22, v13
	v_pk_add_f32 v[22:23], v[18:19], v[22:23]
	v_mov_b32_e32 v25, v17
	v_pk_add_f32 v[8:9], v[8:9], v[22:23]
	v_mov_b32_e32 v3, v23
	v_mov_b32_e32 v5, v9
	v_mov_b32_e32 v13, v8
	v_pk_add_f32 v[4:5], v[4:5], v[14:15] neg_lo:[0,1] neg_hi:[0,1]
	v_pk_add_f32 v[12:13], v[12:13], v[24:25] neg_lo:[0,1] neg_hi:[0,1]
	v_mov_b32_e32 v17, v4
	v_mov_b32_e32 v16, v12
	v_mov_b32_e32 v11, v22
	v_pk_add_f32 v[2:3], v[2:3], v[4:5] neg_lo:[0,1] neg_hi:[0,1]
	v_pk_add_f32 v[4:5], v[18:19], v[16:17] neg_lo:[0,1] neg_hi:[0,1]
	v_mov_b32_e32 v25, v14
	v_pk_add_f32 v[10:11], v[10:11], v[12:13] neg_lo:[0,1] neg_hi:[0,1]
	v_pk_add_f32 v[4:5], v[24:25], v[4:5] neg_lo:[0,1] neg_hi:[0,1]
	v_mov_b32_e32 v12, v10
	v_mov_b32_e32 v13, v2
	v_pk_add_f32 v[4:5], v[12:13], v[4:5]
	v_mov_b32_e32 v2, v11
	v_pk_add_f32 v[2:3], v[4:5], v[2:3]
	v_mov_b32_e32 v7, 0x204
	v_pk_add_f32 v[4:5], v[8:9], v[2:3]
	s_lshl_b32 s3, s70, 3
	v_pk_add_f32 v[8:9], v[4:5], v[8:9] neg_lo:[0,1] neg_hi:[0,1]
	v_lshrrev_b32_e32 v25, 3, v144
	v_pk_add_f32 v[2:3], v[2:3], v[8:9] neg_lo:[0,1] neg_hi:[0,1]
	v_pk_mul_f32 v[8:9], v[0:1], v[4:5]
	v_lshl_add_u32 v6, v145, 14, 0
	v_pk_fma_f32 v[4:5], v[0:1], v[4:5], v[8:9] neg_lo:[0,0,1] neg_hi:[0,0,1]
	v_cmp_class_f32_e32 vcc, v9, v7
	v_pk_fma_f32 v[2:3], v[0:1], v[2:3], v[4:5]
	v_and_b32_e32 v23, 31, v146
	v_pk_add_f32 v[4:5], v[8:9], v[2:3]
	v_lshrrev_b32_e32 v24, 5, v144
	v_pk_add_f32 v[10:11], v[4:5], v[8:9] neg_lo:[0,1] neg_hi:[0,1]
	v_cndmask_b32_e32 v5, v5, v9, vcc
	v_mov_b32_e32 v9, 0x37000000
	v_cmp_eq_f32_e32 vcc, s7, v5
	v_pk_add_f32 v[2:3], v[2:3], v[10:11] neg_lo:[0,1] neg_hi:[0,1]
	v_or_b32_e32 v30, 24, v25
	v_cndmask_b32_e32 v10, 0, v9, vcc
	v_sub_f32_e32 v11, v5, v10
	v_mul_f32_e32 v12, 0x3fb8aa3b, v11
	v_fma_f32 v13, v11, s8, -v12
	v_rndne_f32_e32 v14, v12
	v_fmac_f32_e32 v13, 0x32a5705f, v11
	v_sub_f32_e32 v12, v12, v14
	v_add_f32_e32 v12, v12, v13
	v_exp_f32_e32 v12, v12
	v_cvt_i32_f32_e32 v13, v14
	v_cmp_neq_f32_e64 vcc, |v5|, s6
	s_mov_b32 s58, 0x6dc9c883
	v_or_b32_e32 v27, 8, v25
	v_cndmask_b32_e32 v3, 0, v3, vcc
	v_ldexp_f32 v5, v12, v13
	v_cmp_ngt_f32_e32 vcc, s9, v11
	v_add_f32_e32 v3, v10, v3
	v_mov_b32_e32 v10, 0x7f800000
	v_cndmask_b32_e32 v5, 0, v5, vcc
	v_cmp_nlt_f32_e32 vcc, s7, v11
	v_or_b32_e32 v28, 16, v25
	v_or_b32_e32 v29, 0x1c00, v25
	v_cndmask_b32_e32 v5, v10, v5, vcc
	v_fma_f32 v3, v5, v3, v5
	v_cmp_class_f32_e64 vcc, v5, s10
	s_mov_b64 s[56:57], 0
	s_movk_i32 s72, 0x7ff
	v_cndmask_b32_e32 v3, v3, v5, vcc
	v_and_b32_e32 v5, 0x7fffffff, v3
	v_div_scale_f32 v11, s[0:1], v5, v5, 1.0
	v_rcp_f32_e32 v12, v11
	v_cmp_class_f32_e32 vcc, v8, v7
	s_movk_i32 s73, 0x17ff
	s_mov_b32 s59, 0x3fc45f30
	v_fma_f32 v7, -v11, v12, 1.0
	v_cndmask_b32_e32 v4, v4, v8, vcc
	v_fmac_f32_e32 v12, v7, v12
	v_div_scale_f32 v5, vcc, 1.0, v5, 1.0
	v_mul_f32_e32 v7, v5, v12
	v_fma_f32 v8, -v11, v7, v5
	v_fmac_f32_e32 v7, v8, v12
	v_fma_f32 v5, -v11, v7, v5
	v_div_fmas_f32 v5, v5, v12, v7
	v_cmp_eq_f32_e32 vcc, s7, v4
	v_div_fixup_f32 v3, v5, |v3|, 1.0
	s_movk_i32 s82, 0xfff
	v_cndmask_b32_e32 v7, 0, v9, vcc
	v_sub_f32_e32 v8, v4, v7
	v_mul_f32_e32 v9, 0x3fb8aa3b, v8
	v_fma_f32 v11, v8, s8, -v9
	v_rndne_f32_e32 v12, v9
	v_fmac_f32_e32 v11, 0x32a5705f, v8
	v_sub_f32_e32 v9, v9, v12
	v_add_f32_e32 v9, v9, v11
	v_exp_f32_e32 v9, v9
	v_cvt_i32_f32_e32 v11, v12
	v_cmp_neq_f32_e64 vcc, |v4|, s6
	s_movk_i32 s83, 0x1bff
	s_movk_i32 s84, 0x1c0f
	v_cndmask_b32_e32 v2, 0, v2, vcc
	v_ldexp_f32 v4, v9, v11
	v_cmp_ngt_f32_e32 vcc, s9, v8
	v_add_f32_e32 v2, v7, v2
	s_mov_b32 s85, 0x7fffff80
	v_cndmask_b32_e32 v4, 0, v4, vcc
	v_cmp_nlt_f32_e32 vcc, s7, v8
	s_movk_i32 s86, 0x15ff
	s_movk_i32 s87, 0x1f17
	v_cndmask_b32_e32 v4, v10, v4, vcc
	v_fma_f32 v2, v4, v2, v4
	v_cmp_class_f32_e64 vcc, v4, s10
	v_lshlrev_b32_e32 v10, 2, v25
	s_movk_i32 s88, 0xff37
	v_cndmask_b32_e32 v2, v2, v4, vcc
	v_and_b32_e32 v4, 0x7fffffff, v2
	v_div_scale_f32 v7, s[0:1], v4, v4, 1.0
	v_rcp_f32_e32 v8, v7
	v_cmp_neq_f32_e32 vcc, s6, v1
	s_mov_b64 s[0:1], 0x100000
	s_movk_i32 s89, 0x1f1f
	v_fma_f32 v1, -v7, v8, 1.0
	v_cndmask_b32_e32 v21, 0, v3, vcc
	v_fmac_f32_e32 v8, v1, v8
	v_div_scale_f32 v1, vcc, 1.0, v4, 1.0
	v_mul_f32_e32 v3, v1, v8
	v_fma_f32 v4, -v7, v3, v1
	v_fmac_f32_e32 v3, v4, v8
	v_fma_f32 v1, -v7, v3, v1
	v_div_fmas_f32 v1, v1, v8, v3
	v_cmp_neq_f32_e32 vcc, s6, v0
	s_add_u32 s6, s30, 0xe800000
	s_addc_u32 s7, s31, 0
	s_add_u32 s8, s30, 0xcb00000
	s_addc_u32 s9, s31, 0
	s_add_u32 s10, s26, 0x2c00000
	s_addc_u32 s11, s27, 0
	s_add_u32 s12, s30, 0xb500000
	s_addc_u32 s13, s31, 0
	s_add_u32 s14, s30, 0x9f00000
	s_addc_u32 s15, s31, 0
	s_add_u32 s38, s24, 0x5800000
	s_addc_u32 s39, s25, 0
	s_add_u32 s42, s30, 0x7300000
	v_div_fixup_f32 v1, v1, |v2|, 1.0
	s_addc_u32 s43, s31, 0
	v_cndmask_b32_e32 v22, 0, v1, vcc
	v_lshlrev_b32_e32 v0, 3, v144
	v_mov_b32_e32 v1, 0
	s_add_u32 s44, s30, 0x4700000
	v_lshl_add_u64 v[4:5], s[30:31], 0, v[0:1]
	s_addc_u32 s45, s31, 0
	v_and_b32_e32 v0, 56, v62
	s_add_u32 s52, s30, 0x3700000
	v_mul_u32_u24_e32 v9, 0x84, v0
	s_addc_u32 s53, s31, 0
	v_lshl_add_u32 v7, v23, 2, v6
	v_add3_u32 v26, v6, v9, v10
	v_mov_b32_e32 v6, 0x1c00
	v_lshl_add_u64 v[2:3], v[4:5], 0, s[0:1]
	s_mov_b64 s[0:1], 0x900000
	s_add_u32 s54, s30, 0x2f00000
	v_mul_u32_u24_e32 v8, 0x84, v24
	v_and_or_b32 v31, v30, 15, v6
	v_lshlrev_b32_e32 v6, 6, v145
	v_cmp_gt_u32_e32 vcc, 32, v144
	v_lshl_add_u64 v[4:5], v[4:5], 0, s[0:1]
	s_addc_u32 s55, s31, 0
	v_lshlrev_b32_e32 v32, 6, v20
	s_lshl_b32 s33, s70, 9
	v_add_u32_e32 v33, v7, v8
	v_lshlrev_b32_e32 v6, 1, v0
	s_movk_i32 s90, 0xff3f
	s_mov_b32 s91, 0xc15f
	v_mov_b32_e32 v34, 0xffffea00
	v_mov_b32_e32 v35, 0x80
	v_mov_b32_e32 v36, 0xfffff800
	v_mov_b32_e32 v37, 0x7fff8fc0
	s_branch .LBB0_98
